# grid-barrier seams: acquire-side L1 invalidate issued at arrival (overlaps the wait) instead of after the release is observed
# speedup vs baseline: 1.0195x; 1.0082x over previous
; __device__ __forceinline__ unsigned xb_ld(unsigned* p)              { return __hip_atomic_load(p, __ATOMIC_RELAXED, __HIP_MEMORY_SCOPE_AGENT); }
; __device__ __forceinline__ unsigned xb_add(unsigned* p, unsigned v) { return __hip_atomic_fetch_add(p, v, __ATOMIC_RELAXED, __HIP_MEMORY_SCOPE_AGENT); }
; #define XB_SPIN(cond, bar) do { unsigned _sp = 0; while (cond) { __builtin_amdgcn_s_sleep(1); \
;     if ((++_sp & 255u) == 0u) { if (xb_ld(&(bar)[XB_TMO])) break; if (_sp > XB_SPIN_CAP) { atomicAdd(&(bar)[XB_TMO], 1u); break; } } } } while (0)
; __device__ __forceinline__ void xcd_barrier(const XcdBarrier& b) {
;     asm volatile("s_waitcnt vmcnt(0)" ::: "memory");
;     __syncthreads();
;     if (threadIdx.x == 0) {
;         unsigned* bar = b.bar;
;         __builtin_amdgcn_s_waitcnt(0);
;         unsigned nloc = b.st[0], nx = b.st[1];
;         if (nloc == 0u) { xcd_barrier_complete(bar, b.x, nloc, nx); b.st[0] = nloc; b.st[1] = nx; }
;         const unsigned old = xb_add(&bar[XB_XSUB(b.x)], 1u);
;         const unsigned gen = old / nloc;
;         if (old + 1u == (gen + 1u) * nloc) {
;             __builtin_amdgcn_fence(__ATOMIC_RELEASE, "agent");
;             asm volatile("s_waitcnt vmcnt(0)" ::: "memory");
;             const unsigned og = xb_add(&bar[XB_TOP], 1u);
;             const unsigned tg = og / nx;
;             if (og + 1u == (tg + 1u) * nx) xb_add(&bar[XB_TOPGEN], 1u);
;             else XB_SPIN(xb_ld(&bar[XB_TOPGEN]) == tg, bar);
;             __builtin_amdgcn_fence(__ATOMIC_ACQUIRE, "agent");
;             xb_add(&bar[XB_XGEN(b.x)], 1u);
;             asm volatile("s_waitcnt vmcnt(0)" ::: "memory");
;         } else {
;             XB_SPIN(xb_ld(&bar[XB_XGEN(b.x)]) == gen, bar);
.LBB0_69:
	s_or_b64 exec, exec, s[8:9]
	v_cvt_f32_u32_e32 v6, v4
	s_waitcnt vmcnt(0)
	v_readfirstlane_b32 s2, v5
	v_sub_u32_e32 v5, 0, v4
	v_rcp_iflag_f32_e32 v6, v6
	v_add_u32_e32 v7, s2, v3
	v_mul_f32_e32 v6, 0x4f7ffffe, v6
	v_cvt_u32_f32_e32 v6, v6
	v_mul_lo_u32 v3, v5, v6
	v_mul_hi_u32 v3, v6, v3
	v_add_u32_e32 v3, v6, v3
	v_mul_hi_u32 v3, v7, v3
	v_mul_lo_u32 v5, v3, v4
	v_sub_u32_e32 v5, v7, v5
	v_add_u32_e32 v6, 1, v3
	v_cmp_ge_u32_e32 vcc, v5, v4
	s_nop 1
	v_cndmask_b32_e32 v3, v3, v6, vcc
	v_sub_u32_e32 v6, v5, v4
	v_cndmask_b32_e32 v5, v5, v6, vcc
	v_add_u32_e32 v6, 1, v3
	v_cmp_ge_u32_e32 vcc, v5, v4
	v_add_u32_e32 v5, 1, v7
	s_nop 0
	v_cndmask_b32_e32 v3, v3, v6, vcc
	v_mul_lo_u32 v6, v4, v3
	v_add_u32_e32 v4, v6, v4
	v_cmp_ne_u32_e32 vcc, v5, v4
	s_and_saveexec_b64 s[2:3], vcc
	s_xor_b64 s[6:7], exec, s[2:3]
	s_cbranch_execz .LBB0_83
	s_waitcnt lgkmcnt(0)
	buffer_inv sc1
	v_mov_b32_e32 v2, 0x2000
	global_load_dword v2, v2, s[4:5] offset:1024 sc1
	s_add_u32 s12, s4, 0x2400
	s_addc_u32 s13, s5, 0
	s_waitcnt vmcnt(0)
	v_cmp_eq_u32_e32 vcc, v2, v3
	s_and_saveexec_b64 s[8:9], vcc
	s_cbranch_execz .LBB0_82
	v_readlane_b32 s16, v239, 1
	v_readlane_b32 s18, v239, 3
	v_readlane_b32 s19, v239, 4
	s_add_u32 s10, s18, 0x20200
	v_readlane_b32 s17, v239, 2
	s_addc_u32 s11, s19, 0
	s_mov_b32 s2, 1
	s_mov_b64 s[14:15], 0
	v_mov_b32_e32 v2, 0
	s_branch .LBB0_73

; __device__ __forceinline__ unsigned xb_ld(unsigned* p)              { return __hip_atomic_load(p, __ATOMIC_RELAXED, __HIP_MEMORY_SCOPE_AGENT); }
; __device__ __forceinline__ unsigned xb_add(unsigned* p, unsigned v) { return __hip_atomic_fetch_add(p, v, __ATOMIC_RELAXED, __HIP_MEMORY_SCOPE_AGENT); }
; #define XB_SPIN(cond, bar) do { unsigned _sp = 0; while (cond) { __builtin_amdgcn_s_sleep(1); \
;     if ((++_sp & 255u) == 0u) { if (xb_ld(&(bar)[XB_TMO])) break; if (_sp > XB_SPIN_CAP) { atomicAdd(&(bar)[XB_TMO], 1u); break; } } } } while (0)
; __device__ __forceinline__ void xcd_barrier(const XcdBarrier& b) {
;     ...
;         const unsigned old = xb_add(&bar[XB_XSUB(b.x)], 1u);
;         const unsigned gen = old / nloc;
;         if (old + 1u == (gen + 1u) * nloc) {
;             __builtin_amdgcn_fence(__ATOMIC_RELEASE, "agent");
;             asm volatile("s_waitcnt vmcnt(0)" ::: "memory");
;             const unsigned og = xb_add(&bar[XB_TOP], 1u);
;             const unsigned tg = og / nx;
;             if (og + 1u == (tg + 1u) * nx) xb_add(&bar[XB_TOPGEN], 1u);
;             else XB_SPIN(xb_ld(&bar[XB_TOPGEN]) == tg, bar);
;             __builtin_amdgcn_fence(__ATOMIC_ACQUIRE, "agent");
;             xb_add(&bar[XB_XGEN(b.x)], 1u);
;             asm volatile("s_waitcnt vmcnt(0)" ::: "memory");
;         } else {
;             XB_SPIN(xb_ld(&bar[XB_XGEN(b.x)]) == gen, bar);
;             __builtin_amdgcn_fence(__ATOMIC_ACQUIRE, "agent");
;             asm volatile("s_waitcnt vmcnt(0)" ::: "memory");
.LBB0_82:
	s_or_b64 exec, exec, s[8:9]
	s_waitcnt vmcnt(0)
	s_waitcnt vmcnt(0)
.LBB0_83:
	s_andn2_saveexec_b64 s[2:3], s[6:7]
	s_cbranch_execz .LBB0_103
	s_mov_b64 s[6:7], exec
	buffer_wbl2 sc1
	buffer_inv sc1
	s_waitcnt lgkmcnt(0)
	s_waitcnt vmcnt(0)
	v_mbcnt_lo_u32_b32 v3, s6, 0
	v_mbcnt_hi_u32_b32 v3, s7, v3
	v_cmp_eq_u32_e32 vcc, 0, v3
	s_and_saveexec_b64 s[8:9], vcc
	s_cbranch_execz .LBB0_86
	s_bcnt1_i32_b64 s2, s[6:7]
	v_readlane_b32 s12, v239, 1
	v_mov_b32_e32 v4, 0x23000
	v_mov_b32_e32 v5, s2
	v_readlane_b32 s14, v239, 3
	v_readlane_b32 s15, v239, 4
	v_readlane_b32 s13, v239, 2
	s_nop 3
	global_atomic_add v4, v4, v5, s[14:15] offset:1024 sc0

; __device__ __forceinline__ unsigned xb_ld(unsigned* p)              { return __hip_atomic_load(p, __ATOMIC_RELAXED, __HIP_MEMORY_SCOPE_AGENT); }
; __device__ __forceinline__ unsigned xb_add(unsigned* p, unsigned v) { return __hip_atomic_fetch_add(p, v, __ATOMIC_RELAXED, __HIP_MEMORY_SCOPE_AGENT); }
; #define XB_SPIN(cond, bar) do { unsigned _sp = 0; while (cond) { __builtin_amdgcn_s_sleep(1); \
;     if ((++_sp & 255u) == 0u) { if (xb_ld(&(bar)[XB_TMO])) break; if (_sp > XB_SPIN_CAP) { atomicAdd(&(bar)[XB_TMO], 1u); break; } } } } while (0)
; __device__ __forceinline__ void xcd_barrier(const XcdBarrier& b) {
;     ...
;             const unsigned og = xb_add(&bar[XB_TOP], 1u);
;             const unsigned tg = og / nx;
;             if (og + 1u == (tg + 1u) * nx) xb_add(&bar[XB_TOPGEN], 1u);
;             else XB_SPIN(xb_ld(&bar[XB_TOPGEN]) == tg, bar);
;             __builtin_amdgcn_fence(__ATOMIC_ACQUIRE, "agent");
;             xb_add(&bar[XB_XGEN(b.x)], 1u);
;             asm volatile("s_waitcnt vmcnt(0)" ::: "memory");
.LBB0_100:
	s_or_b64 exec, exec, s[6:7]
	s_mov_b64 s[6:7], exec
	v_mbcnt_lo_u32_b32 v2, s6, 0
	v_mbcnt_hi_u32_b32 v2, s7, v2
	v_cmp_eq_u32_e32 vcc, 0, v2
	s_waitcnt vmcnt(0)
	s_and_saveexec_b64 s[8:9], vcc
	s_cbranch_execz .LBB0_102
	s_bcnt1_i32_b64 s2, s[6:7]
	v_mov_b32_e32 v2, 0x2000
	v_mov_b32_e32 v3, s2
	global_atomic_add v2, v3, s[4:5] offset:1024

; __device__ __forceinline__ unsigned xb_ld(unsigned* p)              { return __hip_atomic_load(p, __ATOMIC_RELAXED, __HIP_MEMORY_SCOPE_AGENT); }
; __device__ __forceinline__ unsigned xb_add(unsigned* p, unsigned v) { return __hip_atomic_fetch_add(p, v, __ATOMIC_RELAXED, __HIP_MEMORY_SCOPE_AGENT); }
; #define XB_SPIN(cond, bar) do { unsigned _sp = 0; while (cond) { __builtin_amdgcn_s_sleep(1); \
;     if ((++_sp & 255u) == 0u) { if (xb_ld(&(bar)[XB_TMO])) break; if (_sp > XB_SPIN_CAP) { atomicAdd(&(bar)[XB_TMO], 1u); break; } } } } while (0)
; __device__ __forceinline__ void xcd_barrier(const XcdBarrier& b) {
;     asm volatile("s_waitcnt vmcnt(0)" ::: "memory");
;     __syncthreads();
;     if (threadIdx.x == 0) {
;         unsigned* bar = b.bar;
;         __builtin_amdgcn_s_waitcnt(0);
;         unsigned nloc = b.st[0], nx = b.st[1];
;         if (nloc == 0u) { xcd_barrier_complete(bar, b.x, nloc, nx); b.st[0] = nloc; b.st[1] = nx; }
;         const unsigned old = xb_add(&bar[XB_XSUB(b.x)], 1u);
;         const unsigned gen = old / nloc;
;         if (old + 1u == (gen + 1u) * nloc) {
;             __builtin_amdgcn_fence(__ATOMIC_RELEASE, "agent");
;             asm volatile("s_waitcnt vmcnt(0)" ::: "memory");
;             const unsigned og = xb_add(&bar[XB_TOP], 1u);
;             const unsigned tg = og / nx;
;             if (og + 1u == (tg + 1u) * nx) xb_add(&bar[XB_TOPGEN], 1u);
;             else XB_SPIN(xb_ld(&bar[XB_TOPGEN]) == tg, bar);
;             __builtin_amdgcn_fence(__ATOMIC_ACQUIRE, "agent");
;             xb_add(&bar[XB_XGEN(b.x)], 1u);
;             asm volatile("s_waitcnt vmcnt(0)" ::: "memory");
;         } else {
;             XB_SPIN(xb_ld(&bar[XB_XGEN(b.x)]) == gen, bar);
.LBB0_825:
	s_or_b64 exec, exec, s[10:11]
	v_cvt_f32_u32_e32 v5, v3
	s_waitcnt vmcnt(0)
	v_readfirstlane_b32 s2, v4
	v_sub_u32_e32 v4, 0, v3
	v_rcp_iflag_f32_e32 v5, v5
	v_add_u32_e32 v6, s2, v2
	v_mul_f32_e32 v5, 0x4f7ffffe, v5
	v_cvt_u32_f32_e32 v5, v5
	v_mul_lo_u32 v2, v4, v5
	v_mul_hi_u32 v2, v5, v2
	v_add_u32_e32 v2, v5, v2
	v_mul_hi_u32 v2, v6, v2
	v_mul_lo_u32 v4, v2, v3
	v_sub_u32_e32 v4, v6, v4
	v_add_u32_e32 v5, 1, v2
	v_cmp_ge_u32_e32 vcc, v4, v3
	s_nop 1
	v_cndmask_b32_e32 v2, v2, v5, vcc
	v_sub_u32_e32 v5, v4, v3
	v_cndmask_b32_e32 v4, v4, v5, vcc
	v_add_u32_e32 v5, 1, v2
	v_cmp_ge_u32_e32 vcc, v4, v3
	v_add_u32_e32 v4, 1, v6
	s_nop 0
	v_cndmask_b32_e32 v2, v2, v5, vcc
	v_mul_lo_u32 v5, v3, v2
	v_add_u32_e32 v3, v5, v3
	v_cmp_ne_u32_e32 vcc, v4, v3
	s_and_saveexec_b64 s[2:3], vcc
	s_xor_b64 s[6:7], exec, s[2:3]
	s_cbranch_execz .LBB0_839
	s_waitcnt lgkmcnt(0)
	buffer_inv sc1
	v_mov_b32_e32 v1, 0x2000
	global_load_dword v1, v1, s[4:5] offset:1024 sc1
	s_add_u32 s14, s4, 0x2400
	s_addc_u32 s15, s5, 0
	s_waitcnt vmcnt(0)
	v_cmp_eq_u32_e32 vcc, v1, v2
	s_and_saveexec_b64 s[10:11], vcc
	s_cbranch_execz .LBB0_838
	v_readlane_b32 s16, v239, 1
	v_readlane_b32 s18, v239, 3
	v_readlane_b32 s17, v239, 2
	v_readlane_b32 s19, v239, 4
	s_add_u32 s12, s18, 0x20200
	s_addc_u32 s13, s19, 0
	s_mov_b32 s2, 1
	s_mov_b64 s[16:17], 0
	v_mov_b32_e32 v1, 0
	s_branch .LBB0_829

; __device__ __forceinline__ unsigned xb_ld(unsigned* p)              { return __hip_atomic_load(p, __ATOMIC_RELAXED, __HIP_MEMORY_SCOPE_AGENT); }
; __device__ __forceinline__ unsigned xb_add(unsigned* p, unsigned v) { return __hip_atomic_fetch_add(p, v, __ATOMIC_RELAXED, __HIP_MEMORY_SCOPE_AGENT); }
; #define XB_SPIN(cond, bar) do { unsigned _sp = 0; while (cond) { __builtin_amdgcn_s_sleep(1); \
;     if ((++_sp & 255u) == 0u) { if (xb_ld(&(bar)[XB_TMO])) break; if (_sp > XB_SPIN_CAP) { atomicAdd(&(bar)[XB_TMO], 1u); break; } } } } while (0)
; __device__ __forceinline__ void xcd_barrier(const XcdBarrier& b) {
;     ...
;         const unsigned old = xb_add(&bar[XB_XSUB(b.x)], 1u);
;         const unsigned gen = old / nloc;
;         if (old + 1u == (gen + 1u) * nloc) {
;             __builtin_amdgcn_fence(__ATOMIC_RELEASE, "agent");
;             asm volatile("s_waitcnt vmcnt(0)" ::: "memory");
;             const unsigned og = xb_add(&bar[XB_TOP], 1u);
;             const unsigned tg = og / nx;
;             if (og + 1u == (tg + 1u) * nx) xb_add(&bar[XB_TOPGEN], 1u);
;             else XB_SPIN(xb_ld(&bar[XB_TOPGEN]) == tg, bar);
;             __builtin_amdgcn_fence(__ATOMIC_ACQUIRE, "agent");
;             xb_add(&bar[XB_XGEN(b.x)], 1u);
;             asm volatile("s_waitcnt vmcnt(0)" ::: "memory");
;         } else {
;             XB_SPIN(xb_ld(&bar[XB_XGEN(b.x)]) == gen, bar);
;             __builtin_amdgcn_fence(__ATOMIC_ACQUIRE, "agent");
;             asm volatile("s_waitcnt vmcnt(0)" ::: "memory");
.LBB0_838:
	s_or_b64 exec, exec, s[10:11]
	s_waitcnt vmcnt(0)
	s_waitcnt vmcnt(0)
.LBB0_839:
	s_andn2_saveexec_b64 s[2:3], s[6:7]
	s_cbranch_execz .LBB0_859
	s_mov_b64 s[6:7], exec
	buffer_wbl2 sc1
	buffer_inv sc1
	s_waitcnt lgkmcnt(0)
	s_waitcnt vmcnt(0)
	v_mbcnt_lo_u32_b32 v2, s6, 0
	v_mbcnt_hi_u32_b32 v2, s7, v2
	v_cmp_eq_u32_e32 vcc, 0, v2
	s_and_saveexec_b64 s[10:11], vcc
	s_cbranch_execz .LBB0_842
	s_bcnt1_i32_b64 s2, s[6:7]
	v_readlane_b32 s12, v239, 1
	v_mov_b32_e32 v3, 0x23000
	v_mov_b32_e32 v4, s2
	v_readlane_b32 s14, v239, 3
	v_readlane_b32 s15, v239, 4
	v_readlane_b32 s13, v239, 2
	s_nop 3
	global_atomic_add v3, v3, v4, s[14:15] offset:1024 sc0

; __device__ __forceinline__ unsigned xb_ld(unsigned* p)              { return __hip_atomic_load(p, __ATOMIC_RELAXED, __HIP_MEMORY_SCOPE_AGENT); }
; __device__ __forceinline__ unsigned xb_add(unsigned* p, unsigned v) { return __hip_atomic_fetch_add(p, v, __ATOMIC_RELAXED, __HIP_MEMORY_SCOPE_AGENT); }
; #define XB_SPIN(cond, bar) do { unsigned _sp = 0; while (cond) { __builtin_amdgcn_s_sleep(1); \
;     if ((++_sp & 255u) == 0u) { if (xb_ld(&(bar)[XB_TMO])) break; if (_sp > XB_SPIN_CAP) { atomicAdd(&(bar)[XB_TMO], 1u); break; } } } } while (0)
; __device__ __forceinline__ void xcd_barrier(const XcdBarrier& b) {
;     ...
;             const unsigned og = xb_add(&bar[XB_TOP], 1u);
;             const unsigned tg = og / nx;
;             if (og + 1u == (tg + 1u) * nx) xb_add(&bar[XB_TOPGEN], 1u);
;             else XB_SPIN(xb_ld(&bar[XB_TOPGEN]) == tg, bar);
;             __builtin_amdgcn_fence(__ATOMIC_ACQUIRE, "agent");
;             xb_add(&bar[XB_XGEN(b.x)], 1u);
;             asm volatile("s_waitcnt vmcnt(0)" ::: "memory");
.LBB0_856:
	s_or_b64 exec, exec, s[6:7]
	s_mov_b64 s[6:7], exec
	v_mbcnt_lo_u32_b32 v1, s6, 0
	v_mbcnt_hi_u32_b32 v1, s7, v1
	v_cmp_eq_u32_e32 vcc, 0, v1
	s_waitcnt vmcnt(0)
	s_and_saveexec_b64 s[10:11], vcc
	s_cbranch_execz .LBB0_858
	s_bcnt1_i32_b64 s2, s[6:7]
	v_mov_b32_e32 v1, 0x2000
	v_mov_b32_e32 v2, s2
	global_atomic_add v1, v2, s[4:5] offset:1024

; __device__ __forceinline__ unsigned xb_ld(unsigned* p)              { return __hip_atomic_load(p, __ATOMIC_RELAXED, __HIP_MEMORY_SCOPE_AGENT); }
; __device__ __forceinline__ unsigned xb_add(unsigned* p, unsigned v) { return __hip_atomic_fetch_add(p, v, __ATOMIC_RELAXED, __HIP_MEMORY_SCOPE_AGENT); }
; #define XB_SPIN(cond, bar) do { unsigned _sp = 0; while (cond) { __builtin_amdgcn_s_sleep(1); \
;     if ((++_sp & 255u) == 0u) { if (xb_ld(&(bar)[XB_TMO])) break; if (_sp > XB_SPIN_CAP) { atomicAdd(&(bar)[XB_TMO], 1u); break; } } } } while (0)
; __device__ __forceinline__ void xcd_barrier(const XcdBarrier& b) {
;     asm volatile("s_waitcnt vmcnt(0)" ::: "memory");
;     __syncthreads();
;     if (threadIdx.x == 0) {
;         unsigned* bar = b.bar;
;         __builtin_amdgcn_s_waitcnt(0);
;         unsigned nloc = b.st[0], nx = b.st[1];
;         if (nloc == 0u) { xcd_barrier_complete(bar, b.x, nloc, nx); b.st[0] = nloc; b.st[1] = nx; }
;         const unsigned old = xb_add(&bar[XB_XSUB(b.x)], 1u);
;         const unsigned gen = old / nloc;
;         if (old + 1u == (gen + 1u) * nloc) {
;             __builtin_amdgcn_fence(__ATOMIC_RELEASE, "agent");
;             asm volatile("s_waitcnt vmcnt(0)" ::: "memory");
;             const unsigned og = xb_add(&bar[XB_TOP], 1u);
;             const unsigned tg = og / nx;
;             if (og + 1u == (tg + 1u) * nx) xb_add(&bar[XB_TOPGEN], 1u);
;             else XB_SPIN(xb_ld(&bar[XB_TOPGEN]) == tg, bar);
;             __builtin_amdgcn_fence(__ATOMIC_ACQUIRE, "agent");
;             xb_add(&bar[XB_XGEN(b.x)], 1u);
;             asm volatile("s_waitcnt vmcnt(0)" ::: "memory");
;         } else {
;             XB_SPIN(xb_ld(&bar[XB_XGEN(b.x)]) == gen, bar);
.LBB0_939:
	s_or_b64 exec, exec, s[12:13]
	v_cvt_f32_u32_e32 v5, v3
	s_waitcnt vmcnt(0)
	v_readfirstlane_b32 s2, v4
	v_sub_u32_e32 v4, 0, v3
	v_rcp_iflag_f32_e32 v5, v5
	v_add_u32_e32 v6, s2, v2
	v_mul_f32_e32 v5, 0x4f7ffffe, v5
	v_cvt_u32_f32_e32 v5, v5
	v_mul_lo_u32 v2, v4, v5
	v_mul_hi_u32 v2, v5, v2
	v_add_u32_e32 v2, v5, v2
	v_mul_hi_u32 v2, v6, v2
	v_mul_lo_u32 v4, v2, v3
	v_sub_u32_e32 v4, v6, v4
	v_add_u32_e32 v5, 1, v2
	v_cmp_ge_u32_e32 vcc, v4, v3
	s_nop 1
	v_cndmask_b32_e32 v2, v2, v5, vcc
	v_sub_u32_e32 v5, v4, v3
	v_cndmask_b32_e32 v4, v4, v5, vcc
	v_add_u32_e32 v5, 1, v2
	v_cmp_ge_u32_e32 vcc, v4, v3
	v_add_u32_e32 v4, 1, v6
	s_nop 0
	v_cndmask_b32_e32 v2, v2, v5, vcc
	v_mul_lo_u32 v5, v3, v2
	v_add_u32_e32 v3, v5, v3
	v_cmp_ne_u32_e32 vcc, v4, v3
	s_and_saveexec_b64 s[2:3], vcc
	s_xor_b64 s[6:7], exec, s[2:3]
	s_cbranch_execz .LBB0_953
	s_waitcnt lgkmcnt(0)
	buffer_inv sc1
	v_mov_b32_e32 v1, 0x2000
	global_load_dword v1, v1, s[4:5] offset:1024 sc1
	s_add_u32 s16, s4, 0x2400
	s_addc_u32 s17, s5, 0
	s_waitcnt vmcnt(0)
	v_cmp_eq_u32_e32 vcc, v1, v2
	s_and_saveexec_b64 s[12:13], vcc
	s_cbranch_execz .LBB0_952
	v_readlane_b32 s20, v239, 1
	v_readlane_b32 s22, v239, 3
	v_readlane_b32 s23, v239, 4
	s_add_u32 s14, s22, 0x20200
	v_readlane_b32 s21, v239, 2
	s_addc_u32 s15, s23, 0
	s_mov_b32 s2, 1
	s_mov_b64 s[18:19], 0
	v_mov_b32_e32 v1, 0
	s_branch .LBB0_943

; __device__ __forceinline__ unsigned xb_ld(unsigned* p)              { return __hip_atomic_load(p, __ATOMIC_RELAXED, __HIP_MEMORY_SCOPE_AGENT); }
; __device__ __forceinline__ unsigned xb_add(unsigned* p, unsigned v) { return __hip_atomic_fetch_add(p, v, __ATOMIC_RELAXED, __HIP_MEMORY_SCOPE_AGENT); }
; #define XB_SPIN(cond, bar) do { unsigned _sp = 0; while (cond) { __builtin_amdgcn_s_sleep(1); \
;     if ((++_sp & 255u) == 0u) { if (xb_ld(&(bar)[XB_TMO])) break; if (_sp > XB_SPIN_CAP) { atomicAdd(&(bar)[XB_TMO], 1u); break; } } } } while (0)
; __device__ __forceinline__ void xcd_barrier(const XcdBarrier& b) {
;     ...
;         const unsigned old = xb_add(&bar[XB_XSUB(b.x)], 1u);
;         const unsigned gen = old / nloc;
;         if (old + 1u == (gen + 1u) * nloc) {
;             __builtin_amdgcn_fence(__ATOMIC_RELEASE, "agent");
;             asm volatile("s_waitcnt vmcnt(0)" ::: "memory");
;             const unsigned og = xb_add(&bar[XB_TOP], 1u);
;             const unsigned tg = og / nx;
;             if (og + 1u == (tg + 1u) * nx) xb_add(&bar[XB_TOPGEN], 1u);
;             else XB_SPIN(xb_ld(&bar[XB_TOPGEN]) == tg, bar);
;             __builtin_amdgcn_fence(__ATOMIC_ACQUIRE, "agent");
;             xb_add(&bar[XB_XGEN(b.x)], 1u);
;             asm volatile("s_waitcnt vmcnt(0)" ::: "memory");
;         } else {
;             XB_SPIN(xb_ld(&bar[XB_XGEN(b.x)]) == gen, bar);
;             __builtin_amdgcn_fence(__ATOMIC_ACQUIRE, "agent");
;             asm volatile("s_waitcnt vmcnt(0)" ::: "memory");
.LBB0_952:
	s_or_b64 exec, exec, s[12:13]
	s_waitcnt vmcnt(0)
	s_waitcnt vmcnt(0)
.LBB0_953:
	s_andn2_saveexec_b64 s[2:3], s[6:7]
	s_cbranch_execz .LBB0_973
	s_mov_b64 s[6:7], exec
	buffer_wbl2 sc1
	buffer_inv sc1
	s_waitcnt lgkmcnt(0)
	s_waitcnt vmcnt(0)
	v_mbcnt_lo_u32_b32 v2, s6, 0
	v_mbcnt_hi_u32_b32 v2, s7, v2
	v_cmp_eq_u32_e32 vcc, 0, v2
	s_and_saveexec_b64 s[12:13], vcc
	s_cbranch_execz .LBB0_956
	s_bcnt1_i32_b64 s2, s[6:7]
	v_readlane_b32 s16, v239, 1
	v_mov_b32_e32 v3, 0x23000
	v_mov_b32_e32 v4, s2
	v_readlane_b32 s18, v239, 3
	v_readlane_b32 s19, v239, 4
	v_readlane_b32 s17, v239, 2
	s_nop 3
	global_atomic_add v3, v3, v4, s[18:19] offset:1024 sc0

; __device__ __forceinline__ unsigned xb_ld(unsigned* p)              { return __hip_atomic_load(p, __ATOMIC_RELAXED, __HIP_MEMORY_SCOPE_AGENT); }
; __device__ __forceinline__ unsigned xb_add(unsigned* p, unsigned v) { return __hip_atomic_fetch_add(p, v, __ATOMIC_RELAXED, __HIP_MEMORY_SCOPE_AGENT); }
; #define XB_SPIN(cond, bar) do { unsigned _sp = 0; while (cond) { __builtin_amdgcn_s_sleep(1); \
;     if ((++_sp & 255u) == 0u) { if (xb_ld(&(bar)[XB_TMO])) break; if (_sp > XB_SPIN_CAP) { atomicAdd(&(bar)[XB_TMO], 1u); break; } } } } while (0)
; __device__ __forceinline__ void xcd_barrier(const XcdBarrier& b) {
;     ...
;             const unsigned og = xb_add(&bar[XB_TOP], 1u);
;             const unsigned tg = og / nx;
;             if (og + 1u == (tg + 1u) * nx) xb_add(&bar[XB_TOPGEN], 1u);
;             else XB_SPIN(xb_ld(&bar[XB_TOPGEN]) == tg, bar);
;             __builtin_amdgcn_fence(__ATOMIC_ACQUIRE, "agent");
;             xb_add(&bar[XB_XGEN(b.x)], 1u);
;             asm volatile("s_waitcnt vmcnt(0)" ::: "memory");
.LBB0_970:
	s_or_b64 exec, exec, s[6:7]
	s_mov_b64 s[6:7], exec
	v_mbcnt_lo_u32_b32 v1, s6, 0
	v_mbcnt_hi_u32_b32 v1, s7, v1
	v_cmp_eq_u32_e32 vcc, 0, v1
	s_waitcnt vmcnt(0)
	s_and_saveexec_b64 s[12:13], vcc
	s_cbranch_execz .LBB0_972
	s_bcnt1_i32_b64 s2, s[6:7]
	v_mov_b32_e32 v1, 0x2000
	v_mov_b32_e32 v2, s2
	global_atomic_add v1, v2, s[4:5] offset:1024
